# barrier 2 skips the L2 write-back (every P1 store is write-through; P0 leftovers were flushed at barrier 1)
# speedup vs baseline: 1.0084x; 1.0030x over previous
; __device__ __forceinline__ unsigned xb_ld(unsigned* p)              { return __hip_atomic_load(p, __ATOMIC_RELAXED, __HIP_MEMORY_SCOPE_AGENT); }
; __device__ __forceinline__ unsigned xb_add(unsigned* p, unsigned v) { return __hip_atomic_fetch_add(p, v, __ATOMIC_RELAXED, __HIP_MEMORY_SCOPE_AGENT); }
; #define XB_SPIN(cond, bar) do { unsigned _sp = 0; while (cond) { __builtin_amdgcn_s_sleep(1); \
;     if ((++_sp & 255u) == 0u) { if (xb_ld(&(bar)[XB_TMO])) break; if (_sp > XB_SPIN_CAP) { atomicAdd(&(bar)[XB_TMO], 1u); break; } } } } while (0)
; __device__ __forceinline__ void xcd_barrier(const XcdBarrier& b) {
;     asm volatile("s_waitcnt vmcnt(0)" ::: "memory");
;     __syncthreads();
;     if (threadIdx.x == 0) {
;         unsigned* bar = b.bar;
;         __builtin_amdgcn_s_waitcnt(0);
;         unsigned nloc = b.st[0], nx = b.st[1];
;         if (nloc == 0u) { xcd_barrier_complete(bar, b.x, nloc, nx); b.st[0] = nloc; b.st[1] = nx; }
;         const unsigned old = xb_add(&bar[XB_XSUB(b.x)], 1u);
;         const unsigned gen = old / nloc;
;         if (old + 1u == (gen + 1u) * nloc) {
;             __builtin_amdgcn_fence(__ATOMIC_RELEASE, "agent");
;             asm volatile("s_waitcnt vmcnt(0)" ::: "memory");
;             const unsigned og = xb_add(&bar[XB_TOP], 1u);
;             const unsigned tg = og / nx;
;             asm volatile("buffer_inv sc1" ::: "memory");
;             if (og + 1u == (tg + 1u) * nx) xb_add(&bar[XB_TOPGEN], 1u);
;             else XB_SPIN(xb_ld(&bar[XB_TOPGEN]) == tg, bar);
;             xb_add(&bar[XB_XGEN(b.x)], 1u);
;             asm volatile("s_waitcnt vmcnt(0)" ::: "memory");
;         } else {
;             asm volatile("buffer_inv sc1" ::: "memory");
;             XB_SPIN(xb_ld(&bar[XB_XGEN(b.x)]) == gen, bar);
;             asm volatile("s_waitcnt vmcnt(0)" ::: "memory");
;         }
;     }
;     __syncthreads();
; }
.Lgb_body:
	v_mov_b32_e32 v0, 0
	s_waitcnt vmcnt(0) lgkmcnt(0)
	ds_read_b32 v2, v0
	ds_read_b32 v1, v0 offset:4
	s_getreg_b32 s75, hwreg(HW_REG_XCC_ID, 0, 4)
	s_and_b32 s75, s75, 15
	s_lshl_b32 s75, s75, 8
	s_add_u32 s76, s58, 0xc938000
	s_addc_u32 s77, s59, 0
	s_add_u32 s78, s76, s75
	s_addc_u32 s79, s77, 0
	v_mov_b32_e32 v3, 0x1000
	v_mov_b32_e32 v4, 1
	s_nop 3
	global_atomic_add v3, v3, v4, s[78:79] offset:1024 sc0
	s_waitcnt lgkmcnt(0)
	s_nop 0
	v_readfirstlane_b32 s80, v2
	v_readfirstlane_b32 s81, v1
	s_add_i32 s82, s73, 1
	s_mul_i32 s83, s82, s80
	s_waitcnt vmcnt(0)
	s_nop 0
	v_readfirstlane_b32 s84, v3
	s_add_i32 s84, s84, 1
	s_cmp_lg_u32 s84, s83
	s_cbranch_scc1 .Lgb_wait
	s_cmp_eq_u32 s73, 1
	s_cbranch_scc1 .Lgb_nowb
	buffer_wbl2 sc1
.Lgb_nowb:
	s_waitcnt vmcnt(0) lgkmcnt(0)
	v_mov_b32_e32 v3, 0x3000
	v_mov_b32_e32 v4, 1
	global_atomic_add v3, v3, v4, s[76:77] offset:1024 sc0
	buffer_inv sc1
	s_mul_i32 s85, s82, s81
	s_waitcnt vmcnt(0)
	s_nop 0
	v_readfirstlane_b32 s86, v3
	s_add_i32 s86, s86, 1
	s_cmp_lg_u32 s86, s85
	s_cbranch_scc1 .Lgb_leadwait
	v_mov_b32_e32 v3, 0x3000
	global_atomic_add v3, v4, s[76:77] offset:1280
	s_mov_b64 exec, 0xffff
	v_mbcnt_lo_u32_b32 v0, -1, 0
	v_lshlrev_b32_e32 v0, 8, v0
	v_add_u32_e32 v0, 0x2400, v0
	v_mov_b32_e32 v1, 1
	global_atomic_add v0, v1, s[76:77]
	s_mov_b64 exec, 1
	s_branch .Lgb_done
